# v47 + gates_phase: 32 row loads issued at once, MFMA accumulate chain, bias pointer and biases prefetched (run 1)
# baseline (speedup 1.0000x reference)
.LBB0_126:
	s_mov_b32 s6, s18
	s_lshl_b32 s6, s6, 3
	s_add_i32 s6, s6, s17
	s_mul_i32 s7, s6, s16
	s_add_i32 s7, s22, s7
	s_cmpk_gt_i32 s7, 0x7ff
	s_cbranch_scc1 .LBB0_136
	s_mul_i32 s6, s23, s6
	v_add_u32_e32 v16, s6, v18
	v_ashrrev_i32_e32 v17, 31, v16
	v_lshlrev_b64 v[2:3], 11, v[16:17]
	v_lshl_add_u64 v[2:3], v[10:11], 0, v[2:3]
	global_load_dwordx2 v[106:107], v[14:15], off
	global_load_dwordx4 v[86:89], v[2:3], off
	global_load_dwordx4 v[90:93], v[2:3], off offset:64
	global_load_dwordx4 v[94:97], v[2:3], off offset:128
	global_load_dwordx4 v[98:101], v[2:3], off offset:192
	global_load_dwordx4 v[102:105], v[2:3], off offset:256
	global_load_dwordx4 v[110:113], v[2:3], off offset:320
	global_load_dwordx4 v[116:119], v[2:3], off offset:384
	global_load_dwordx4 v[120:123], v[2:3], off offset:448
	global_load_dwordx4 v[124:127], v[2:3], off offset:512
	global_load_dwordx4 v[128:131], v[2:3], off offset:576
	global_load_dwordx4 v[132:135], v[2:3], off offset:640
	global_load_dwordx4 v[136:139], v[2:3], off offset:704
	global_load_dwordx4 v[140:143], v[2:3], off offset:768
	global_load_dwordx4 v[144:147], v[2:3], off offset:832
	global_load_dwordx4 v[148:151], v[2:3], off offset:896
	global_load_dwordx4 v[152:155], v[2:3], off offset:960
	global_load_dwordx4 v[156:159], v[2:3], off offset:1024
	global_load_dwordx4 v[160:163], v[2:3], off offset:1088
	global_load_dwordx4 v[164:167], v[2:3], off offset:1152
	global_load_dwordx4 v[168:171], v[2:3], off offset:1216
	global_load_dwordx4 v[172:175], v[2:3], off offset:1280
	global_load_dwordx4 v[176:179], v[2:3], off offset:1344
	global_load_dwordx4 v[180:183], v[2:3], off offset:1408
	global_load_dwordx4 v[184:187], v[2:3], off offset:1472
	global_load_dwordx4 v[190:193], v[2:3], off offset:1536
	global_load_dwordx4 v[194:197], v[2:3], off offset:1600
	global_load_dwordx4 v[198:201], v[2:3], off offset:1664
	global_load_dwordx4 v[202:205], v[2:3], off offset:1728
	global_load_dwordx4 v[206:209], v[2:3], off offset:1792
	global_load_dwordx4 v[210:213], v[2:3], off offset:1856
	global_load_dwordx4 v[214:217], v[2:3], off offset:1920
	global_load_dwordx4 v[218:221], v[2:3], off offset:1984
	ds_read_b128 v[50:53], v0
	ds_read_b128 v[54:57], v19
	ds_read_b128 v[58:61], v20
	ds_read_b128 v[62:65], v21
	ds_read_b128 v[66:69], v22
	ds_read_b128 v[70:73], v23
	ds_read_b128 v[74:77], v24
	ds_read_b128 v[78:81], v25
	s_waitcnt vmcnt(24) lgkmcnt(0)
	v_lshl_add_u64 v[106:107], s[34:35], 2, v[106:107]
	global_load_dwordx4 v[82:85], v[106:107], off
	v_mfma_f32_16x16x32_bf16 v[4:7], v[50:53], v[86:89], 0
	v_mfma_f32_16x16x32_bf16 v[4:7], v[54:57], v[90:93], v[4:7]
	v_mfma_f32_16x16x32_bf16 v[4:7], v[58:61], v[94:97], v[4:7]
	v_mfma_f32_16x16x32_bf16 v[4:7], v[62:65], v[98:101], v[4:7]
	v_mfma_f32_16x16x32_bf16 v[4:7], v[66:69], v[102:105], v[4:7]
	v_mfma_f32_16x16x32_bf16 v[4:7], v[70:73], v[110:113], v[4:7]
	v_mfma_f32_16x16x32_bf16 v[4:7], v[74:77], v[116:119], v[4:7]
	v_mfma_f32_16x16x32_bf16 v[4:7], v[78:81], v[120:123], v[4:7]
	ds_read_b128 v[50:53], v26
	ds_read_b128 v[54:57], v27
	ds_read_b128 v[58:61], v28
	ds_read_b128 v[62:65], v29
	ds_read_b128 v[66:69], v30
	ds_read_b128 v[70:73], v31
	ds_read_b128 v[74:77], v32
	ds_read_b128 v[78:81], v33
	s_waitcnt vmcnt(17) lgkmcnt(0)
	v_mfma_f32_16x16x32_bf16 v[4:7], v[50:53], v[124:127], v[4:7]
	v_mfma_f32_16x16x32_bf16 v[4:7], v[54:57], v[128:131], v[4:7]
	v_mfma_f32_16x16x32_bf16 v[4:7], v[58:61], v[132:135], v[4:7]
	v_mfma_f32_16x16x32_bf16 v[4:7], v[62:65], v[136:139], v[4:7]
	v_mfma_f32_16x16x32_bf16 v[4:7], v[66:69], v[140:143], v[4:7]
	v_mfma_f32_16x16x32_bf16 v[4:7], v[70:73], v[144:147], v[4:7]
	v_mfma_f32_16x16x32_bf16 v[4:7], v[74:77], v[148:151], v[4:7]
	v_mfma_f32_16x16x32_bf16 v[4:7], v[78:81], v[152:155], v[4:7]
	ds_read_b128 v[50:53], v34
	ds_read_b128 v[54:57], v35
	ds_read_b128 v[58:61], v36
	ds_read_b128 v[62:65], v37
	ds_read_b128 v[66:69], v38
	ds_read_b128 v[70:73], v39
	ds_read_b128 v[74:77], v40
	ds_read_b128 v[78:81], v41
	s_waitcnt vmcnt(9) lgkmcnt(0)
	v_mfma_f32_16x16x32_bf16 v[4:7], v[50:53], v[156:159], v[4:7]
	v_mfma_f32_16x16x32_bf16 v[4:7], v[54:57], v[160:163], v[4:7]
	v_mfma_f32_16x16x32_bf16 v[4:7], v[58:61], v[164:167], v[4:7]
	v_mfma_f32_16x16x32_bf16 v[4:7], v[62:65], v[168:171], v[4:7]
	v_mfma_f32_16x16x32_bf16 v[4:7], v[66:69], v[172:175], v[4:7]
	v_mfma_f32_16x16x32_bf16 v[4:7], v[70:73], v[176:179], v[4:7]
	v_mfma_f32_16x16x32_bf16 v[4:7], v[74:77], v[180:183], v[4:7]
	v_mfma_f32_16x16x32_bf16 v[4:7], v[78:81], v[184:187], v[4:7]
	ds_read_b128 v[50:53], v42
	ds_read_b128 v[54:57], v43
	ds_read_b128 v[58:61], v44
	ds_read_b128 v[62:65], v45
	ds_read_b128 v[66:69], v46
	ds_read_b128 v[70:73], v47
	ds_read_b128 v[74:77], v48
	ds_read_b128 v[78:81], v49
	s_waitcnt vmcnt(1) lgkmcnt(0)
	v_mfma_f32_16x16x32_bf16 v[4:7], v[50:53], v[190:193], v[4:7]
	v_mfma_f32_16x16x32_bf16 v[4:7], v[54:57], v[194:197], v[4:7]
	v_mfma_f32_16x16x32_bf16 v[4:7], v[58:61], v[198:201], v[4:7]
	v_mfma_f32_16x16x32_bf16 v[4:7], v[62:65], v[202:205], v[4:7]
	v_mfma_f32_16x16x32_bf16 v[4:7], v[66:69], v[206:209], v[4:7]
	v_mfma_f32_16x16x32_bf16 v[4:7], v[70:73], v[210:213], v[4:7]
	v_mfma_f32_16x16x32_bf16 v[4:7], v[74:77], v[214:217], v[4:7]
	v_mfma_f32_16x16x32_bf16 v[2:5], v[78:81], v[218:221], v[4:7]
	s_and_saveexec_b64 s[12:13], s[2:3]
	s_cbranch_execz .LBB0_125
	s_nop 0
	v_lshlrev_b64 v[8:9], 6, v[16:17]
	v_lshl_add_u64 v[8:9], s[82:83], 0, v[8:9]
	global_load_dwordx4 v[50:53], v[8:9], off
	global_load_dwordx4 v[54:57], v[8:9], off offset:32
	global_load_dwordx4 v[58:61], v[8:9], off offset:16
	global_load_dwordx4 v[62:65], v[8:9], off offset:48
	s_mov_b32 s6, 0x800000
	s_waitcnt vmcnt(3)
	v_mov_b32_e32 v8, v50
	s_nop 0
	v_mov_b32_e32 v6, v82
	s_waitcnt vmcnt(2)
	v_mov_b32_e32 v9, v54
	v_mov_b32_e32 v54, v51
	v_mov_b32_e32 v50, v52
	v_mov_b32_e32 v51, v56
	v_mov_b32_e32 v56, v53
	s_waitcnt vmcnt(1)
	v_mov_b32_e32 v52, v58
	s_waitcnt vmcnt(0)
	v_mov_b32_e32 v53, v62
	v_mov_b32_e32 v62, v59
	v_mov_b32_e32 v58, v60
	v_mov_b32_e32 v59, v64
	v_mov_b32_e32 v64, v61
	v_pk_add_f32 v[8:9], v[8:9], v[54:55]
	v_pk_add_f32 v[50:51], v[50:51], v[56:57]
	v_pk_add_f32 v[52:53], v[52:53], v[62:63]
	v_pk_add_f32 v[54:55], v[58:59], v[64:65]
	v_pk_add_f32 v[8:9], v[8:9], v[50:51]
	v_pk_add_f32 v[50:51], v[52:53], v[54:55]
	s_nop 0
	v_pk_add_f32 v[8:9], v[8:9], v[50:51]
	s_nop 0
	v_add_f32_e32 v7, v8, v9
	v_fmamk_f32 v7, v7, 0x3a800000, v224
	v_mul_f32_e32 v8, 0x4b800000, v7
	v_cmp_gt_f32_e32 vcc, s6, v7
	s_nop 1
	v_cndmask_b32_e32 v7, v7, v8, vcc
	v_rsq_f32_e32 v7, v7
	s_nop 0
	v_mul_f32_e32 v8, 0x45800000, v7
	v_cndmask_b32_e32 v50, v7, v8, vcc
	v_mov_b64_e32 v[8:9], s[10:11]
	s_waitcnt vmcnt(0)
	v_fmac_f32_e32 v6, v50, v2
	s_and_saveexec_b64 s[6:7], s[4:5]
	s_cbranch_execz .LBB0_130
	s_mov_b32 s14, 0xbfb8aa3b
	v_mul_f32_e64 v2, |v6|, s14
	v_exp_f32_e32 v2, v2
	s_mov_b32 s14, 0x800000
	v_max_f32_e32 v6, v6, v6
	v_min_f32_e32 v6, 0, v6
	v_add_f32_e32 v2, 1.0, v2
	v_cmp_gt_f32_e32 vcc, s14, v2
	s_mov_b32 s14, 0x3f317217
	s_nop 0
	v_cndmask_b32_e64 v7, 0, 32, vcc
	v_ldexp_f32 v2, v2, v7
	v_log_f32_e32 v2, v2
	v_cndmask_b32_e32 v7, 0, v227, vcc
	v_mul_f32_e32 v8, 0x3f317217, v2
	v_fma_f32 v8, v2, s14, -v8
	v_fmac_f32_e32 v8, 0x3377d1cf, v2
	s_mov_b32 s14, 0x7f800000
	v_fmac_f32_e32 v8, 0x3f317217, v2
	v_cmp_lt_f32_e64 vcc, |v2|, s14
	s_nop 1
	v_cndmask_b32_e32 v2, v2, v8, vcc
	v_sub_f32_e32 v2, v2, v7
	v_sub_f32_e32 v6, v6, v2
	v_mov_b64_e32 v[8:9], s[8:9]
.LBB0_130:
	s_or_b64 exec, exec, s[6:7]
	s_nop 0
	s_waitcnt vmcnt(0)
	s_nop 0
	v_mov_b32_e32 v7, v83
	s_waitcnt vmcnt(0)
	v_fmac_f32_e32 v7, v50, v3
	v_mov_b64_e32 v[2:3], s[10:11]
	s_and_saveexec_b64 s[6:7], s[4:5]
	s_cbranch_execz .LBB0_132
	s_mov_b32 s14, 0xbfb8aa3b
	v_mul_f32_e64 v2, |v7|, s14
	v_exp_f32_e32 v2, v2
	s_mov_b32 s14, 0x800000
	v_add_f32_e32 v2, 1.0, v2
	v_cmp_gt_f32_e32 vcc, s14, v2
	s_mov_b32 s14, 0x3f317217
	s_nop 0
	v_cndmask_b32_e64 v3, 0, 32, vcc
	v_ldexp_f32 v2, v2, v3
	v_log_f32_e32 v2, v2
	v_max_f32_e32 v3, v7, v7
	v_cndmask_b32_e32 v7, 0, v227, vcc
	v_min_f32_e32 v3, 0, v3
	v_mul_f32_e32 v8, 0x3f317217, v2
	v_fma_f32 v8, v2, s14, -v8
	v_fmac_f32_e32 v8, 0x3377d1cf, v2
	s_mov_b32 s14, 0x7f800000
	v_fmac_f32_e32 v8, 0x3f317217, v2
	v_cmp_lt_f32_e64 vcc, |v2|, s14
	s_nop 1
	v_cndmask_b32_e32 v2, v2, v8, vcc
	v_sub_f32_e32 v2, v2, v7
	v_sub_f32_e32 v7, v3, v2
	v_mov_b64_e32 v[2:3], s[8:9]
.LBB0_132:
	s_or_b64 exec, exec, s[6:7]
	s_nop 0
	s_waitcnt vmcnt(0)
	s_nop 0
	v_mov_b32_e32 v8, v84
	v_mov_b64_e32 v[2:3], s[10:11]
	s_waitcnt vmcnt(0)
	v_fmac_f32_e32 v8, v50, v4
	s_and_saveexec_b64 s[6:7], s[4:5]
	s_cbranch_execz .LBB0_134
	s_mov_b32 s14, 0xbfb8aa3b
	v_mul_f32_e64 v2, |v8|, s14
	v_exp_f32_e32 v2, v2
	s_mov_b32 s14, 0x800000
	v_add_f32_e32 v2, 1.0, v2
	v_cmp_gt_f32_e32 vcc, s14, v2
	s_mov_b32 s14, 0x3f317217
	s_nop 0
	v_cndmask_b32_e64 v3, 0, 32, vcc
	v_ldexp_f32 v2, v2, v3
	v_log_f32_e32 v2, v2
	v_max_f32_e32 v3, v8, v8
	v_cndmask_b32_e32 v4, 0, v227, vcc
	v_min_f32_e32 v3, 0, v3
	v_mul_f32_e32 v8, 0x3f317217, v2
	v_fma_f32 v8, v2, s14, -v8
	v_fmac_f32_e32 v8, 0x3377d1cf, v2
	s_mov_b32 s14, 0x7f800000
	v_fmac_f32_e32 v8, 0x3f317217, v2
	v_cmp_lt_f32_e64 vcc, |v2|, s14
	s_nop 1
	v_cndmask_b32_e32 v2, v2, v8, vcc
	v_sub_f32_e32 v2, v2, v4
	v_sub_f32_e32 v8, v3, v2
	v_mov_b64_e32 v[2:3], s[8:9]
.LBB0_134:
	s_or_b64 exec, exec, s[6:7]
	s_nop 0
	s_waitcnt vmcnt(0)
	s_nop 0
	v_mov_b32_e32 v9, v85
	s_waitcnt vmcnt(0)
	v_fmac_f32_e32 v9, v50, v5
	s_and_saveexec_b64 s[14:15], s[4:5]
	s_cbranch_execz .LBB0_124
	s_mov_b32 s6, 0xbfb8aa3b
	v_mul_f32_e64 v2, |v9|, s6
	v_exp_f32_e32 v2, v2
	s_mov_b32 s6, 0x800000
	v_add_f32_e32 v2, 1.0, v2
	v_cmp_gt_f32_e32 vcc, s6, v2
	s_mov_b32 s6, 0x3f317217
	s_nop 0
	v_cndmask_b32_e64 v3, 0, 32, vcc
	v_ldexp_f32 v2, v2, v3
	v_log_f32_e32 v2, v2
	v_max_f32_e32 v3, v9, v9
	v_min_f32_e32 v3, 0, v3
	v_mul_f32_e32 v4, 0x3f317217, v2
	v_fma_f32 v4, v2, s6, -v4
	v_fmac_f32_e32 v4, 0x3377d1cf, v2
	s_mov_b32 s6, 0x7f800000
	v_fmac_f32_e32 v4, 0x3f317217, v2
	v_cmp_lt_f32_e64 s[6:7], |v2|, s6
	s_nop 1
	v_cndmask_b32_e64 v2, v2, v4, s[6:7]
	v_cndmask_b32_e32 v4, 0, v227, vcc
	v_sub_f32_e32 v2, v2, v4
	v_sub_f32_e32 v9, v3, v2
	s_branch .LBB0_124

.LBB0_385:
	s_mov_b32 s6, s18
	s_lshl_b32 s6, s6, 3
	s_add_i32 s6, s6, s17
	s_mul_i32 s7, s6, s16
	s_add_i32 s7, s22, s7
	s_cmpk_gt_i32 s7, 0x7ff
	s_cbranch_scc1 .LBB0_395
	s_mul_i32 s6, s23, s6
	v_add_u32_e32 v16, s6, v18
	v_ashrrev_i32_e32 v17, 31, v16
	v_lshlrev_b64 v[2:3], 11, v[16:17]
	v_lshl_add_u64 v[2:3], v[10:11], 0, v[2:3]
	global_load_dwordx2 v[106:107], v[14:15], off
	global_load_dwordx4 v[86:89], v[2:3], off
	global_load_dwordx4 v[90:93], v[2:3], off offset:64
	global_load_dwordx4 v[94:97], v[2:3], off offset:128
	global_load_dwordx4 v[98:101], v[2:3], off offset:192
	global_load_dwordx4 v[102:105], v[2:3], off offset:256
	global_load_dwordx4 v[110:113], v[2:3], off offset:320
	global_load_dwordx4 v[116:119], v[2:3], off offset:384
	global_load_dwordx4 v[120:123], v[2:3], off offset:448
	global_load_dwordx4 v[124:127], v[2:3], off offset:512
	global_load_dwordx4 v[128:131], v[2:3], off offset:576
	global_load_dwordx4 v[132:135], v[2:3], off offset:640
	global_load_dwordx4 v[136:139], v[2:3], off offset:704
	global_load_dwordx4 v[140:143], v[2:3], off offset:768
	global_load_dwordx4 v[144:147], v[2:3], off offset:832
	global_load_dwordx4 v[148:151], v[2:3], off offset:896
	global_load_dwordx4 v[152:155], v[2:3], off offset:960
	global_load_dwordx4 v[156:159], v[2:3], off offset:1024
	global_load_dwordx4 v[160:163], v[2:3], off offset:1088
	global_load_dwordx4 v[164:167], v[2:3], off offset:1152
	global_load_dwordx4 v[168:171], v[2:3], off offset:1216
	global_load_dwordx4 v[172:175], v[2:3], off offset:1280
	global_load_dwordx4 v[176:179], v[2:3], off offset:1344
	global_load_dwordx4 v[180:183], v[2:3], off offset:1408
	global_load_dwordx4 v[184:187], v[2:3], off offset:1472
	global_load_dwordx4 v[190:193], v[2:3], off offset:1536
	global_load_dwordx4 v[194:197], v[2:3], off offset:1600
	global_load_dwordx4 v[198:201], v[2:3], off offset:1664
	global_load_dwordx4 v[202:205], v[2:3], off offset:1728
	global_load_dwordx4 v[206:209], v[2:3], off offset:1792
	global_load_dwordx4 v[210:213], v[2:3], off offset:1856
	global_load_dwordx4 v[214:217], v[2:3], off offset:1920
	global_load_dwordx4 v[218:221], v[2:3], off offset:1984
	ds_read_b128 v[50:53], v0
	ds_read_b128 v[54:57], v19
	ds_read_b128 v[58:61], v20
	ds_read_b128 v[62:65], v21
	ds_read_b128 v[66:69], v22
	ds_read_b128 v[70:73], v23
	ds_read_b128 v[74:77], v24
	ds_read_b128 v[78:81], v25
	s_waitcnt vmcnt(24) lgkmcnt(0)
	v_lshl_add_u64 v[106:107], s[34:35], 2, v[106:107]
	global_load_dwordx4 v[82:85], v[106:107], off
	v_mfma_f32_16x16x32_bf16 v[4:7], v[50:53], v[86:89], 0
	v_mfma_f32_16x16x32_bf16 v[4:7], v[54:57], v[90:93], v[4:7]
	v_mfma_f32_16x16x32_bf16 v[4:7], v[58:61], v[94:97], v[4:7]
	v_mfma_f32_16x16x32_bf16 v[4:7], v[62:65], v[98:101], v[4:7]
	v_mfma_f32_16x16x32_bf16 v[4:7], v[66:69], v[102:105], v[4:7]
	v_mfma_f32_16x16x32_bf16 v[4:7], v[70:73], v[110:113], v[4:7]
	v_mfma_f32_16x16x32_bf16 v[4:7], v[74:77], v[116:119], v[4:7]
	v_mfma_f32_16x16x32_bf16 v[4:7], v[78:81], v[120:123], v[4:7]
	ds_read_b128 v[50:53], v26
	ds_read_b128 v[54:57], v27
	ds_read_b128 v[58:61], v28
	ds_read_b128 v[62:65], v29
	ds_read_b128 v[66:69], v30
	ds_read_b128 v[70:73], v31
	ds_read_b128 v[74:77], v32
	ds_read_b128 v[78:81], v33
	s_waitcnt vmcnt(17) lgkmcnt(0)
	v_mfma_f32_16x16x32_bf16 v[4:7], v[50:53], v[124:127], v[4:7]
	v_mfma_f32_16x16x32_bf16 v[4:7], v[54:57], v[128:131], v[4:7]
	v_mfma_f32_16x16x32_bf16 v[4:7], v[58:61], v[132:135], v[4:7]
	v_mfma_f32_16x16x32_bf16 v[4:7], v[62:65], v[136:139], v[4:7]
	v_mfma_f32_16x16x32_bf16 v[4:7], v[66:69], v[140:143], v[4:7]
	v_mfma_f32_16x16x32_bf16 v[4:7], v[70:73], v[144:147], v[4:7]
	v_mfma_f32_16x16x32_bf16 v[4:7], v[74:77], v[148:151], v[4:7]
	v_mfma_f32_16x16x32_bf16 v[4:7], v[78:81], v[152:155], v[4:7]
	ds_read_b128 v[50:53], v34
	ds_read_b128 v[54:57], v35
	ds_read_b128 v[58:61], v36
	ds_read_b128 v[62:65], v37
	ds_read_b128 v[66:69], v38
	ds_read_b128 v[70:73], v39
	ds_read_b128 v[74:77], v40
	ds_read_b128 v[78:81], v41
	s_waitcnt vmcnt(9) lgkmcnt(0)
	v_mfma_f32_16x16x32_bf16 v[4:7], v[50:53], v[156:159], v[4:7]
	v_mfma_f32_16x16x32_bf16 v[4:7], v[54:57], v[160:163], v[4:7]
	v_mfma_f32_16x16x32_bf16 v[4:7], v[58:61], v[164:167], v[4:7]
	v_mfma_f32_16x16x32_bf16 v[4:7], v[62:65], v[168:171], v[4:7]
	v_mfma_f32_16x16x32_bf16 v[4:7], v[66:69], v[172:175], v[4:7]
	v_mfma_f32_16x16x32_bf16 v[4:7], v[70:73], v[176:179], v[4:7]
	v_mfma_f32_16x16x32_bf16 v[4:7], v[74:77], v[180:183], v[4:7]
	v_mfma_f32_16x16x32_bf16 v[4:7], v[78:81], v[184:187], v[4:7]
	ds_read_b128 v[50:53], v42
	ds_read_b128 v[54:57], v43
	ds_read_b128 v[58:61], v44
	ds_read_b128 v[62:65], v45
	ds_read_b128 v[66:69], v46
	ds_read_b128 v[70:73], v47
	ds_read_b128 v[74:77], v48
	ds_read_b128 v[78:81], v49
	s_waitcnt vmcnt(1) lgkmcnt(0)
	v_mfma_f32_16x16x32_bf16 v[4:7], v[50:53], v[190:193], v[4:7]
	v_mfma_f32_16x16x32_bf16 v[4:7], v[54:57], v[194:197], v[4:7]
	v_mfma_f32_16x16x32_bf16 v[4:7], v[58:61], v[198:201], v[4:7]
	v_mfma_f32_16x16x32_bf16 v[4:7], v[62:65], v[202:205], v[4:7]
	v_mfma_f32_16x16x32_bf16 v[4:7], v[66:69], v[206:209], v[4:7]
	v_mfma_f32_16x16x32_bf16 v[4:7], v[70:73], v[210:213], v[4:7]
	v_mfma_f32_16x16x32_bf16 v[4:7], v[74:77], v[214:217], v[4:7]
	v_mfma_f32_16x16x32_bf16 v[2:5], v[78:81], v[218:221], v[4:7]
	s_and_saveexec_b64 s[12:13], s[2:3]
	s_cbranch_execz .LBB0_384
	v_lshlrev_b64 v[6:7], 6, v[16:17]
	v_lshl_add_u64 v[58:59], s[82:83], 0, v[6:7]
	global_load_dwordx4 v[6:9], v[58:59], off offset:16
	global_load_dwordx4 v[50:53], v[58:59], off offset:48
	global_load_dwordx4 v[54:57], v[58:59], off
	s_nop 0
	global_load_dwordx4 v[58:61], v[58:59], off offset:32
	s_mov_b32 s6, 0x800000
	s_waitcnt vmcnt(1)
	v_mov_b32_e32 v62, v54
	s_waitcnt vmcnt(0)
	v_mov_b32_e32 v63, v58
	v_mov_b32_e32 v58, v55
	v_pk_add_f32 v[54:55], v[62:63], v[58:59]
	v_mov_b32_e32 v58, v56
	v_mov_b32_e32 v59, v60
	v_mov_b32_e32 v60, v57
	v_pk_add_f32 v[56:57], v[58:59], v[60:61]
	s_nop 0
	v_pk_add_f32 v[54:55], v[54:55], v[56:57]
	v_mov_b32_e32 v56, v6
	v_mov_b32_e32 v57, v50
	v_mov_b32_e32 v50, v7
	v_pk_add_f32 v[6:7], v[56:57], v[50:51]
	v_mov_b32_e32 v50, v8
	v_mov_b32_e32 v51, v52
	v_mov_b32_e32 v52, v9
	v_pk_add_f32 v[8:9], v[50:51], v[52:53]
	s_nop 0
	v_pk_add_f32 v[6:7], v[6:7], v[8:9]
	v_mov_b64_e32 v[8:9], s[10:11]
	v_pk_add_f32 v[6:7], v[54:55], v[6:7]
	s_nop 0
	v_add_f32_e32 v6, v6, v7
	v_fmamk_f32 v6, v6, 0x3a800000, v224
	v_cmp_gt_f32_e32 vcc, s6, v6
	v_mul_f32_e32 v7, 0x4b800000, v6
	s_nop 0
	v_cndmask_b32_e32 v6, v6, v7, vcc
	v_rsq_f32_e32 v6, v6
	s_nop 0
	v_mul_f32_e32 v7, 0x45800000, v6
	v_cndmask_b32_e32 v50, v6, v7, vcc
	s_nop 0
	s_waitcnt vmcnt(0)
	s_nop 0
	v_mov_b32_e32 v6, v82
	s_waitcnt vmcnt(0)
	v_fmac_f32_e32 v6, v50, v2
	s_and_saveexec_b64 s[6:7], s[4:5]
	s_cbranch_execz .LBB0_389
	s_mov_b32 s14, 0xbfb8aa3b
	v_mul_f32_e64 v2, |v6|, s14
	v_exp_f32_e32 v2, v2
	s_mov_b32 s14, 0x800000
	v_max_f32_e32 v6, v6, v6
	v_min_f32_e32 v6, 0, v6
	v_add_f32_e32 v2, 1.0, v2
	v_cmp_gt_f32_e32 vcc, s14, v2
	s_mov_b32 s14, 0x3f317217
	s_nop 0
	v_cndmask_b32_e64 v7, 0, 32, vcc
	v_ldexp_f32 v2, v2, v7
	v_log_f32_e32 v2, v2
	v_cndmask_b32_e32 v7, 0, v227, vcc
	v_mul_f32_e32 v8, 0x3f317217, v2
	v_fma_f32 v8, v2, s14, -v8
	v_fmac_f32_e32 v8, 0x3377d1cf, v2
	s_mov_b32 s14, 0x7f800000
	v_fmac_f32_e32 v8, 0x3f317217, v2
	v_cmp_lt_f32_e64 vcc, |v2|, s14
	s_nop 1
	v_cndmask_b32_e32 v2, v2, v8, vcc
	v_sub_f32_e32 v2, v2, v7
	v_sub_f32_e32 v6, v6, v2
	v_mov_b64_e32 v[8:9], s[8:9]
